# GEMM K-loops: MFMA-phase priority dropped four MFMA groups (16 MFMAs) before the phase ends
# speedup vs baseline: 1.0438x; 1.0037x over previous
.LBB0_677:
	s_add_i32 s10, s10, 64
	s_waitcnt lgkmcnt(2)
	v_mfma_f32_16x16x32_bf16 v[162:165], v[202:205], v[178:181], v[162:165]
	v_mfma_f32_16x16x32_bf16 v[154:157], v[202:205], v[182:185], v[154:157]
	v_mfma_f32_16x16x32_bf16 v[134:137], v[202:205], v[186:189], v[134:137]
	v_mfma_f32_16x16x32_bf16 v[114:117], v[202:205], v[190:193], v[114:117]
	ds_read_b128 v[202:205], v216 offset:8192
	s_waitcnt lgkmcnt(2)
	v_mfma_f32_16x16x32_bf16 v[82:85], v[198:201], v[190:193], v[82:85]
	v_mfma_f32_16x16x32_bf16 v[86:89], v[198:201], v[186:189], v[86:89]
	v_mfma_f32_16x16x32_bf16 v[90:93], v[198:201], v[182:185], v[90:93]
	v_mfma_f32_16x16x32_bf16 v[94:97], v[198:201], v[178:181], v[94:97]
	ds_read_b128 v[198:201], v216 offset:10240
	s_waitcnt lgkmcnt(2)
	v_mfma_f32_16x16x32_bf16 v[78:81], v[194:197], v[178:181], v[78:81]
	v_mfma_f32_16x16x32_bf16 v[74:77], v[194:197], v[182:185], v[74:77]
	v_mfma_f32_16x16x32_bf16 v[70:73], v[194:197], v[186:189], v[70:73]
	v_mfma_f32_16x16x32_bf16 v[66:69], v[194:197], v[190:193], v[66:69]
	ds_read_b128 v[194:197], v216 offset:12288
	s_setprio 0
	s_waitcnt lgkmcnt(2)
	v_mfma_f32_16x16x32_bf16 v[50:53], v[202:205], v[190:193], v[50:53]
	v_mfma_f32_16x16x32_bf16 v[54:57], v[202:205], v[186:189], v[54:57]
	v_mfma_f32_16x16x32_bf16 v[58:61], v[202:205], v[182:185], v[58:61]
	v_mfma_f32_16x16x32_bf16 v[62:65], v[202:205], v[178:181], v[62:65]
	ds_read_b128 v[202:205], v216 offset:14336
	s_waitcnt lgkmcnt(2)
	v_mfma_f32_16x16x32_bf16 v[46:49], v[198:201], v[178:181], v[46:49]
	v_mfma_f32_16x16x32_bf16 v[42:45], v[198:201], v[182:185], v[42:45]
	v_mfma_f32_16x16x32_bf16 v[38:41], v[198:201], v[186:189], v[38:41]
	v_mfma_f32_16x16x32_bf16 v[34:37], v[198:201], v[190:193], v[34:37]
	s_waitcnt lgkmcnt(1)
	v_mfma_f32_16x16x32_bf16 v[6:9], v[194:197], v[190:193], v[6:9]
	v_mfma_f32_16x16x32_bf16 v[18:21], v[194:197], v[186:189], v[18:21]
	v_mfma_f32_16x16x32_bf16 v[26:29], v[194:197], v[182:185], v[26:29]
	v_mfma_f32_16x16x32_bf16 v[30:33], v[194:197], v[178:181], v[30:33]
	s_waitcnt lgkmcnt(0)
	v_mfma_f32_16x16x32_bf16 v[22:25], v[202:205], v[178:181], v[22:25]
	v_mfma_f32_16x16x32_bf16 v[14:17], v[202:205], v[182:185], v[14:17]
	v_mfma_f32_16x16x32_bf16 v[10:13], v[202:205], v[186:189], v[10:13]
	v_mfma_f32_16x16x32_bf16 v[2:5], v[202:205], v[190:193], v[2:5]
	s_add_u32 s38, s38, 0x80
	s_addc_u32 s39, s39, 0
	s_add_u32 s40, s40, 0x80
	s_addc_u32 s41, s41, 0
	s_and_b64 vcc, exec, s[52:53]
	s_cbranch_vccnz .LBB0_684

.LBB0_1483:
	s_add_i32 s1, s1, 64
	s_waitcnt lgkmcnt(2)
	v_mfma_f32_16x16x32_bf16 v[162:165], v[202:205], v[178:181], v[162:165]
	v_mfma_f32_16x16x32_bf16 v[154:157], v[202:205], v[182:185], v[154:157]
	v_mfma_f32_16x16x32_bf16 v[122:125], v[202:205], v[186:189], v[122:125]
	v_mfma_f32_16x16x32_bf16 v[106:109], v[202:205], v[190:193], v[106:109]
	ds_read_b128 v[202:205], v216 offset:8192
	s_waitcnt lgkmcnt(2)
	v_mfma_f32_16x16x32_bf16 v[82:85], v[198:201], v[190:193], v[82:85]
	v_mfma_f32_16x16x32_bf16 v[86:89], v[198:201], v[186:189], v[86:89]
	v_mfma_f32_16x16x32_bf16 v[90:93], v[198:201], v[182:185], v[90:93]
	v_mfma_f32_16x16x32_bf16 v[94:97], v[198:201], v[178:181], v[94:97]
	ds_read_b128 v[198:201], v216 offset:10240
	s_waitcnt lgkmcnt(2)
	v_mfma_f32_16x16x32_bf16 v[78:81], v[194:197], v[178:181], v[78:81]
	v_mfma_f32_16x16x32_bf16 v[74:77], v[194:197], v[182:185], v[74:77]
	v_mfma_f32_16x16x32_bf16 v[70:73], v[194:197], v[186:189], v[70:73]
	v_mfma_f32_16x16x32_bf16 v[66:69], v[194:197], v[190:193], v[66:69]
	ds_read_b128 v[194:197], v216 offset:12288
	s_setprio 0
	s_waitcnt lgkmcnt(2)
	v_mfma_f32_16x16x32_bf16 v[50:53], v[202:205], v[190:193], v[50:53]
	v_mfma_f32_16x16x32_bf16 v[54:57], v[202:205], v[186:189], v[54:57]
	v_mfma_f32_16x16x32_bf16 v[58:61], v[202:205], v[182:185], v[58:61]
	v_mfma_f32_16x16x32_bf16 v[62:65], v[202:205], v[178:181], v[62:65]
	ds_read_b128 v[202:205], v216 offset:14336
	s_waitcnt lgkmcnt(2)
	v_mfma_f32_16x16x32_bf16 v[46:49], v[198:201], v[178:181], v[46:49]
	v_mfma_f32_16x16x32_bf16 v[42:45], v[198:201], v[182:185], v[42:45]
	v_mfma_f32_16x16x32_bf16 v[38:41], v[198:201], v[186:189], v[38:41]
	v_mfma_f32_16x16x32_bf16 v[34:37], v[198:201], v[190:193], v[34:37]
	s_waitcnt lgkmcnt(1)
	v_mfma_f32_16x16x32_bf16 v[6:9], v[194:197], v[190:193], v[6:9]
	v_mfma_f32_16x16x32_bf16 v[18:21], v[194:197], v[186:189], v[18:21]
	v_mfma_f32_16x16x32_bf16 v[26:29], v[194:197], v[182:185], v[26:29]
	v_mfma_f32_16x16x32_bf16 v[30:33], v[194:197], v[178:181], v[30:33]
	s_waitcnt lgkmcnt(0)
	v_mfma_f32_16x16x32_bf16 v[22:25], v[202:205], v[178:181], v[22:25]
	v_mfma_f32_16x16x32_bf16 v[14:17], v[202:205], v[182:185], v[14:17]
	v_mfma_f32_16x16x32_bf16 v[10:13], v[202:205], v[186:189], v[10:13]
	v_mfma_f32_16x16x32_bf16 v[2:5], v[202:205], v[190:193], v[2:5]
	s_add_u32 s38, s38, 0x80
	s_addc_u32 s39, s39, 0
	s_add_u32 s40, s40, 0x80
	s_addc_u32 s41, s41, 0
	s_and_b64 vcc, exec, s[44:45]
	s_cbranch_vccnz .LBB0_1490

.LBB0_1681:
	s_waitcnt lgkmcnt(2)
	v_mfma_f32_16x16x32_bf16 v[162:165], v[202:205], v[178:181], v[162:165]
	v_mfma_f32_16x16x32_bf16 v[166:169], v[202:205], v[182:185], v[166:169]
	v_mfma_f32_16x16x32_bf16 v[170:173], v[202:205], v[186:189], v[170:173]
	v_mfma_f32_16x16x32_bf16 v[174:177], v[202:205], v[190:193], v[174:177]
	ds_read_b128 v[202:205], v217 offset:8192
	s_waitcnt lgkmcnt(2)
	v_mfma_f32_16x16x32_bf16 v[158:161], v[198:201], v[190:193], v[158:161]
	v_mfma_f32_16x16x32_bf16 v[154:157], v[198:201], v[186:189], v[154:157]
	v_mfma_f32_16x16x32_bf16 v[150:153], v[198:201], v[182:185], v[150:153]
	v_mfma_f32_16x16x32_bf16 v[146:149], v[198:201], v[178:181], v[146:149]
	ds_read_b128 v[198:201], v217 offset:10240
	s_waitcnt lgkmcnt(2)
	v_mfma_f32_16x16x32_bf16 v[118:121], v[194:197], v[178:181], v[118:121]
	v_mfma_f32_16x16x32_bf16 v[122:125], v[194:197], v[182:185], v[122:125]
	v_mfma_f32_16x16x32_bf16 v[126:129], v[194:197], v[186:189], v[126:129]
	v_mfma_f32_16x16x32_bf16 v[130:133], v[194:197], v[190:193], v[130:133]
	ds_read_b128 v[194:197], v217 offset:12288
	s_setprio 0
	s_waitcnt lgkmcnt(2)
	v_mfma_f32_16x16x32_bf16 v[110:113], v[202:205], v[190:193], v[110:113]
	v_mfma_f32_16x16x32_bf16 v[106:109], v[202:205], v[186:189], v[106:109]
	v_mfma_f32_16x16x32_bf16 v[102:105], v[202:205], v[182:185], v[102:105]
	v_mfma_f32_16x16x32_bf16 v[98:101], v[202:205], v[178:181], v[98:101]
	ds_read_b128 v[202:205], v217 offset:14336
	s_waitcnt lgkmcnt(2)
	v_mfma_f32_16x16x32_bf16 v[82:85], v[198:201], v[178:181], v[82:85]
	v_mfma_f32_16x16x32_bf16 v[86:89], v[198:201], v[182:185], v[86:89]
	v_mfma_f32_16x16x32_bf16 v[90:93], v[198:201], v[186:189], v[90:93]
	v_mfma_f32_16x16x32_bf16 v[94:97], v[198:201], v[190:193], v[94:97]
	s_waitcnt lgkmcnt(1)
	v_mfma_f32_16x16x32_bf16 v[78:81], v[194:197], v[190:193], v[78:81]
	v_mfma_f32_16x16x32_bf16 v[74:77], v[194:197], v[186:189], v[74:77]
	v_mfma_f32_16x16x32_bf16 v[70:73], v[194:197], v[182:185], v[70:73]
	v_mfma_f32_16x16x32_bf16 v[66:69], v[194:197], v[178:181], v[66:69]
	s_waitcnt lgkmcnt(0)
	v_mfma_f32_16x16x32_bf16 v[50:53], v[202:205], v[178:181], v[50:53]
	v_mfma_f32_16x16x32_bf16 v[54:57], v[202:205], v[182:185], v[54:57]
	v_mfma_f32_16x16x32_bf16 v[58:61], v[202:205], v[186:189], v[58:61]
	v_mfma_f32_16x16x32_bf16 v[62:65], v[202:205], v[190:193], v[62:65]
	s_add_u32 s36, s36, 0x80
	s_addc_u32 s37, s37, 0
	s_add_u32 s38, s38, 0x80
	s_addc_u32 s39, s39, 0
	s_cmpk_gt_u32 s1, 0x3bf
	s_cbranch_scc1 .LBB0_1686

.LBB0_1814:
	s_add_i32 s20, s20, 64
	s_waitcnt lgkmcnt(2)
	v_mfma_f32_16x16x32_bf16 v[162:165], v[202:205], v[178:181], v[162:165]
	v_mfma_f32_16x16x32_bf16 v[154:157], v[202:205], v[182:185], v[154:157]
	v_mfma_f32_16x16x32_bf16 v[118:121], v[202:205], v[186:189], v[118:121]
	v_mfma_f32_16x16x32_bf16 v[106:109], v[202:205], v[190:193], v[106:109]
	ds_read_b128 v[202:205], v216 offset:8192
	s_waitcnt lgkmcnt(2)
	v_mfma_f32_16x16x32_bf16 v[82:85], v[198:201], v[190:193], v[82:85]
	v_mfma_f32_16x16x32_bf16 v[86:89], v[198:201], v[186:189], v[86:89]
	v_mfma_f32_16x16x32_bf16 v[90:93], v[198:201], v[182:185], v[90:93]
	v_mfma_f32_16x16x32_bf16 v[94:97], v[198:201], v[178:181], v[94:97]
	ds_read_b128 v[198:201], v216 offset:10240
	s_waitcnt lgkmcnt(2)
	v_mfma_f32_16x16x32_bf16 v[78:81], v[194:197], v[178:181], v[78:81]
	v_mfma_f32_16x16x32_bf16 v[74:77], v[194:197], v[182:185], v[74:77]
	v_mfma_f32_16x16x32_bf16 v[70:73], v[194:197], v[186:189], v[70:73]
	v_mfma_f32_16x16x32_bf16 v[66:69], v[194:197], v[190:193], v[66:69]
	ds_read_b128 v[194:197], v216 offset:12288
	s_setprio 0
	s_waitcnt lgkmcnt(2)
	v_mfma_f32_16x16x32_bf16 v[50:53], v[202:205], v[190:193], v[50:53]
	v_mfma_f32_16x16x32_bf16 v[54:57], v[202:205], v[186:189], v[54:57]
	v_mfma_f32_16x16x32_bf16 v[58:61], v[202:205], v[182:185], v[58:61]
	v_mfma_f32_16x16x32_bf16 v[62:65], v[202:205], v[178:181], v[62:65]
	ds_read_b128 v[202:205], v216 offset:14336
	s_waitcnt lgkmcnt(2)
	v_mfma_f32_16x16x32_bf16 v[46:49], v[198:201], v[178:181], v[46:49]
	v_mfma_f32_16x16x32_bf16 v[42:45], v[198:201], v[182:185], v[42:45]
	v_mfma_f32_16x16x32_bf16 v[38:41], v[198:201], v[186:189], v[38:41]
	v_mfma_f32_16x16x32_bf16 v[34:37], v[198:201], v[190:193], v[34:37]
	s_waitcnt lgkmcnt(1)
	v_mfma_f32_16x16x32_bf16 v[6:9], v[194:197], v[190:193], v[6:9]
	v_mfma_f32_16x16x32_bf16 v[18:21], v[194:197], v[186:189], v[18:21]
	v_mfma_f32_16x16x32_bf16 v[26:29], v[194:197], v[182:185], v[26:29]
	v_mfma_f32_16x16x32_bf16 v[30:33], v[194:197], v[178:181], v[30:33]
	s_waitcnt lgkmcnt(0)
	v_mfma_f32_16x16x32_bf16 v[22:25], v[202:205], v[178:181], v[22:25]
	v_mfma_f32_16x16x32_bf16 v[14:17], v[202:205], v[182:185], v[14:17]
	v_mfma_f32_16x16x32_bf16 v[10:13], v[202:205], v[186:189], v[10:13]
	v_mfma_f32_16x16x32_bf16 v[2:5], v[202:205], v[190:193], v[2:5]
	s_add_u32 s36, s36, 0x80
	s_addc_u32 s37, s37, 0
	s_add_u32 s38, s38, 0x80
	s_addc_u32 s39, s39, 0
	s_and_b64 vcc, exec, s[40:41]
	s_cbranch_vccnz .LBB0_1821
